# P5 down-GEMM epilogue: all 16 residual loads issued up front before ALIGN barrier, counted vmcnt, no store-to-load serialisation
# speedup vs baseline: 1.0077x; 1.0077x over previous
; #define PG8_STAGE(bufoff, gbase, voff) do { _Pragma("unroll") for (int _i = 0; _i < 2; ++_i) \
;         __builtin_amdgcn_global_load_lds((const unsigned*)((const char*)(gbase) + (voff)[_i]), (PG8_LAS unsigned*)(lds + (bufoff) + ldsw + _i * 8192), 16, 0, 0); } while (0)
; #define PG8_LDA(dst, b, h) do { _Pragma("unroll") for (int m = 0; m < 4; ++m) _Pragma("unroll") for (int k = 0; k < 2; ++k) dst[m][k] = *(const PG8_LAS bf16x8*)(lds + PG8_SA(b, h) + aoff + m * 2048 + k * 1024); } while (0)
; #define PG8_LDB(dst, b, h) do { _Pragma("unroll") for (int n = 0; n < 2; ++n) _Pragma("unroll") for (int k = 0; k < 2; ++k) dst[n][k] = *(const PG8_LAS bf16x8*)(lds + PG8_SB(b, h) + boff + n * 2048 + k * 1024); } while (0)
; #define PG8_MMA(ai, bj, At, Bt) do { __builtin_amdgcn_s_setprio(1); _Pragma("unroll") for (int m = 0; m < 4; ++m) _Pragma("unroll") for (int n = 0; n < 2; ++n) _Pragma("unroll") for (int k = 0; k < 2; ++k) \
;         acc[ai][bj][m][n] = __builtin_amdgcn_mfma_f32_16x16x32_bf16(Bt[n][k], At[m][k], acc[ai][bj][m][n], 0, 0, 0); __builtin_amdgcn_s_setprio(0); } while (0)
; #define PG8_WAIT_V(n) asm volatile("s_waitcnt vmcnt(" #n ")" ::: "memory")
; #define PG8_WAIT_L(n) asm volatile("s_waitcnt lgkmcnt(" #n ")" ::: "memory")
; #define PG8_BAR __builtin_amdgcn_s_barrier()
; #define PG8_SCHED __builtin_amdgcn_sched_barrier(0)
; template <class Epi, class Sched, bool ALIGN_EPI = false, bool SP2 = false>
; __device__ __forceinline__ void gemm_phase(PG8_LAS unsigned char* lds, const Gemm g, const Sched& S, const Epi& E) {
;     ...
;             PG8_LDB(B0, 0, 0); PG8_LDB(B1, 0, 1); PG8_SCHED; PG8_LDA(At, 0, 0); PG8_STAGE(PG8_SA(1, 1), a1 + hstep, voffA);
;             PG8_WAIT_V(8); PG8_WAIT_L(0); PG8_BAR; PG8_MMA(0, 0, At, B0); PG8_MMA(0, 1, At, B1); PG8_BAR; PG8_SCHED;
;             PG8_LDA(At, 0, 1); PG8_STAGE(PG8_SB(0, 0), b2, voffB); PG8_STAGE(PG8_SB(0, 1), b2 + hstep, voffB); PG8_STAGE(PG8_SA(0, 0), a2, voffA);
;             PG8_WAIT_V(8); PG8_WAIT_L(0); PG8_BAR; PG8_MMA(1, 0, At, B0); PG8_MMA(1, 1, At, B1); PG8_BAR; PG8_SCHED;
.LBB0_1498:
	ds_read_b128 v[142:145], v148
	ds_read_b128 v[154:157], v148 offset:1024
	ds_read_b128 v[158:161], v148 offset:2048
	ds_read_b128 v[162:165], v148 offset:3072
	ds_read_b128 v[166:169], v149
	ds_read_b128 v[170:173], v149 offset:1024
	ds_read_b128 v[174:177], v149 offset:2048
	ds_read_b128 v[178:181], v149 offset:3072
	s_add_u32 s24, s22, 0xfff00080
	s_addc_u32 s25, s23, -1
	s_cmp_eq_u32 s47, 60
	s_cselect_b32 s27, s11, s25
	s_cselect_b32 s26, s43, s24
	s_cselect_b32 s25, s9, s46
	s_cselect_b32 s24, s44, s45
	v_lshl_add_u64 v[214:215], s[22:23], 0, v[136:137]
	s_add_i32 m0, s19, 0xc000
	ds_read_b128 v[182:185], v150
	ds_read_b128 v[186:189], v150 offset:1024
	ds_read_b128 v[190:193], v150 offset:2048
	ds_read_b128 v[194:197], v150 offset:3072
	ds_read_b128 v[198:201], v150 offset:4096
	ds_read_b128 v[202:205], v150 offset:5120
	ds_read_b128 v[206:209], v150 offset:6144
	ds_read_b128 v[210:213], v150 offset:7168
	global_load_lds_dwordx4 v[214:215], off
	v_lshl_add_u64 v[214:215], s[22:23], 0, v[138:139]
	s_add_i32 m0, s19, 0xe000
	s_nop 0
	global_load_lds_dwordx4 v[214:215], off
	s_waitcnt vmcnt(8)
	s_waitcnt lgkmcnt(0)
	s_barrier
	s_setprio 1
	s_waitcnt lgkmcnt(0)
	v_mfma_f32_16x16x32_bf16 v[124:127], v[142:145], v[182:185], v[124:127]
	v_mfma_f32_16x16x32_bf16 v[120:123], v[158:161], v[182:185], v[120:123]
	v_mfma_f32_16x16x32_bf16 v[108:111], v[142:145], v[190:193], v[108:111]
	v_mfma_f32_16x16x32_bf16 v[104:107], v[158:161], v[190:193], v[104:107]
	v_mfma_f32_16x16x32_bf16 v[92:95], v[142:145], v[198:201], v[92:95]
	v_mfma_f32_16x16x32_bf16 v[88:91], v[158:161], v[198:201], v[88:91]
	v_mfma_f32_16x16x32_bf16 v[76:79], v[142:145], v[206:209], v[76:79]
	v_mfma_f32_16x16x32_bf16 v[72:75], v[158:161], v[206:209], v[72:75]
	v_mfma_f32_16x16x32_bf16 v[124:127], v[154:157], v[186:189], v[124:127]
	v_mfma_f32_16x16x32_bf16 v[120:123], v[162:165], v[186:189], v[120:123]
	v_mfma_f32_16x16x32_bf16 v[108:111], v[154:157], v[194:197], v[108:111]
	v_mfma_f32_16x16x32_bf16 v[104:107], v[162:165], v[194:197], v[104:107]
	v_mfma_f32_16x16x32_bf16 v[92:95], v[154:157], v[202:205], v[92:95]
	v_mfma_f32_16x16x32_bf16 v[88:91], v[162:165], v[202:205], v[88:91]
	v_mfma_f32_16x16x32_bf16 v[76:79], v[154:157], v[210:213], v[76:79]
	v_mfma_f32_16x16x32_bf16 v[72:75], v[162:165], v[210:213], v[72:75]
	s_setprio 0
	s_setprio 1
	v_mfma_f32_16x16x32_bf16 v[116:119], v[166:169], v[182:185], v[116:119]
	v_mfma_f32_16x16x32_bf16 v[112:115], v[174:177], v[182:185], v[112:115]
	v_mfma_f32_16x16x32_bf16 v[100:103], v[166:169], v[190:193], v[100:103]
	v_mfma_f32_16x16x32_bf16 v[96:99], v[174:177], v[190:193], v[96:99]
	v_mfma_f32_16x16x32_bf16 v[84:87], v[166:169], v[198:201], v[84:87]
	v_mfma_f32_16x16x32_bf16 v[80:83], v[174:177], v[198:201], v[80:83]
	v_mfma_f32_16x16x32_bf16 v[68:71], v[166:169], v[206:209], v[68:71]
	v_mfma_f32_16x16x32_bf16 v[64:67], v[174:177], v[206:209], v[64:67]
	v_mfma_f32_16x16x32_bf16 v[116:119], v[170:173], v[186:189], v[116:119]
	v_mfma_f32_16x16x32_bf16 v[112:115], v[178:181], v[186:189], v[112:115]
	v_mfma_f32_16x16x32_bf16 v[100:103], v[170:173], v[194:197], v[100:103]
	v_mfma_f32_16x16x32_bf16 v[96:99], v[178:181], v[194:197], v[96:99]
	v_mfma_f32_16x16x32_bf16 v[84:87], v[170:173], v[202:205], v[84:87]
	v_mfma_f32_16x16x32_bf16 v[80:83], v[178:181], v[202:205], v[80:83]
	v_mfma_f32_16x16x32_bf16 v[68:71], v[170:173], v[210:213], v[68:71]
	v_mfma_f32_16x16x32_bf16 v[64:67], v[178:181], v[210:213], v[64:67]
	s_setprio 0
	s_barrier
	s_add_i32 s48, s37, s29
	v_lshl_add_u64 v[214:215], s[24:25], 0, v[130:131]
	s_mov_b32 m0, s48
	ds_read_b128 v[182:185], v150 offset:16384
	ds_read_b128 v[186:189], v150 offset:17408
	ds_read_b128 v[190:193], v150 offset:18432
	ds_read_b128 v[194:197], v150 offset:19456
	ds_read_b128 v[198:201], v150 offset:20480
	ds_read_b128 v[202:205], v150 offset:21504
	ds_read_b128 v[206:209], v150 offset:22528
	ds_read_b128 v[210:213], v150 offset:23552
	global_load_lds_dwordx4 v[214:215], off
	s_add_i32 m0, s48, 0x2000
	s_add_u32 s48, s24, 0x100000
	v_lshl_add_u64 v[216:217], s[24:25], 0, v[134:135]
	s_addc_u32 s49, s25, 0
	s_add_i32 s52, s38, s29
	global_load_lds_dwordx4 v[216:217], off
	v_lshl_add_u64 v[218:219], s[48:49], 0, v[130:131]
	s_mov_b32 m0, s52
	v_lshl_add_u64 v[220:221], s[26:27], 0, v[132:133]
	global_load_lds_dwordx4 v[218:219], off
	v_lshl_add_u64 v[218:219], s[48:49], 0, v[134:135]
	s_add_i32 m0, s52, 0x2000
	s_nop 0
	global_load_lds_dwordx4 v[218:219], off
	v_lshl_add_u64 v[218:219], s[26:27], 0, v[128:129]
	s_mov_b32 m0, s19
	s_nop 0
	global_load_lds_dwordx4 v[218:219], off
	s_mov_b32 m0, s21
	s_nop 0
	global_load_lds_dwordx4 v[220:221], off
	s_waitcnt vmcnt(8)
	s_waitcnt lgkmcnt(0)
	s_barrier
; #define PG8_STAGE(bufoff, gbase, voff) do { _Pragma("unroll") for (int _i = 0; _i < 2; ++_i) \
;         __builtin_amdgcn_global_load_lds((const unsigned*)((const char*)(gbase) + (voff)[_i]), (PG8_LAS unsigned*)(lds + (bufoff) + ldsw + _i * 8192), 16, 0, 0); } while (0)
; #define PG8_LDA(dst, b, h) do { _Pragma("unroll") for (int m = 0; m < 4; ++m) _Pragma("unroll") for (int k = 0; k < 2; ++k) dst[m][k] = *(const PG8_LAS bf16x8*)(lds + PG8_SA(b, h) + aoff + m * 2048 + k * 1024); } while (0)
; #define PG8_LDB(dst, b, h) do { _Pragma("unroll") for (int n = 0; n < 2; ++n) _Pragma("unroll") for (int k = 0; k < 2; ++k) dst[n][k] = *(const PG8_LAS bf16x8*)(lds + PG8_SB(b, h) + boff + n * 2048 + k * 1024); } while (0)
; #define PG8_MMA(ai, bj, At, Bt) do { __builtin_amdgcn_s_setprio(1); _Pragma("unroll") for (int m = 0; m < 4; ++m) _Pragma("unroll") for (int n = 0; n < 2; ++n) _Pragma("unroll") for (int k = 0; k < 2; ++k) \
;         acc[ai][bj][m][n] = __builtin_amdgcn_mfma_f32_16x16x32_bf16(Bt[n][k], At[m][k], acc[ai][bj][m][n], 0, 0, 0); __builtin_amdgcn_s_setprio(0); } while (0)
; #define PG8_WAIT_V(n) asm volatile("s_waitcnt vmcnt(" #n ")" ::: "memory")
; #define PG8_WAIT_L(n) asm volatile("s_waitcnt lgkmcnt(" #n ")" ::: "memory")
; #define PG8_BAR __builtin_amdgcn_s_barrier()
; #define PG8_SCHED __builtin_amdgcn_sched_barrier(0)
; template <class Epi, class Sched, bool ALIGN_EPI = false, bool SP2 = false>
; __device__ __forceinline__ void gemm_phase(PG8_LAS unsigned char* lds, const Gemm g, const Sched& S, const Epi& E) {
;     ...
;             PG8_WAIT_V(8); PG8_WAIT_L(0); PG8_BAR; PG8_MMA(1, 0, At, B0); PG8_MMA(1, 1, At, B1); PG8_BAR; PG8_SCHED;
;             PG8_LDB(B0, 1, 0); PG8_LDB(B1, 1, 1); PG8_SCHED; PG8_LDA(At, 1, 0); PG8_STAGE(PG8_SA(0, 1), a2 + hstep, voffA);
;             PG8_WAIT_V(8); PG8_WAIT_L(0); PG8_BAR; PG8_MMA(0, 0, At, B0); PG8_MMA(0, 1, At, B1); PG8_BAR; PG8_SCHED;
	s_setprio 1
	s_waitcnt lgkmcnt(0)
	v_mfma_f32_16x16x32_bf16 v[60:63], v[142:145], v[182:185], v[60:63]
	v_mfma_f32_16x16x32_bf16 v[56:59], v[158:161], v[182:185], v[56:59]
	v_mfma_f32_16x16x32_bf16 v[44:47], v[142:145], v[190:193], v[44:47]
	v_mfma_f32_16x16x32_bf16 v[40:43], v[158:161], v[190:193], v[40:43]
	v_mfma_f32_16x16x32_bf16 v[28:31], v[142:145], v[198:201], v[28:31]
	v_mfma_f32_16x16x32_bf16 v[24:27], v[158:161], v[198:201], v[24:27]
	v_mfma_f32_16x16x32_bf16 v[12:15], v[142:145], v[206:209], v[12:15]
	v_mfma_f32_16x16x32_bf16 v[8:11], v[158:161], v[206:209], v[8:11]
	v_mfma_f32_16x16x32_bf16 v[60:63], v[154:157], v[186:189], v[60:63]
	v_mfma_f32_16x16x32_bf16 v[56:59], v[162:165], v[186:189], v[56:59]
	v_mfma_f32_16x16x32_bf16 v[44:47], v[154:157], v[194:197], v[44:47]
	v_mfma_f32_16x16x32_bf16 v[40:43], v[162:165], v[194:197], v[40:43]
	v_mfma_f32_16x16x32_bf16 v[28:31], v[154:157], v[202:205], v[28:31]
	v_mfma_f32_16x16x32_bf16 v[24:27], v[162:165], v[202:205], v[24:27]
	v_mfma_f32_16x16x32_bf16 v[12:15], v[154:157], v[210:213], v[12:15]
	v_mfma_f32_16x16x32_bf16 v[8:11], v[162:165], v[210:213], v[8:11]
	s_setprio 0
	s_setprio 1
	v_mfma_f32_16x16x32_bf16 v[52:55], v[166:169], v[182:185], v[52:55]
	v_mfma_f32_16x16x32_bf16 v[48:51], v[174:177], v[182:185], v[48:51]
	v_mfma_f32_16x16x32_bf16 v[36:39], v[166:169], v[190:193], v[36:39]
	v_mfma_f32_16x16x32_bf16 v[32:35], v[174:177], v[190:193], v[32:35]
	v_mfma_f32_16x16x32_bf16 v[20:23], v[166:169], v[198:201], v[20:23]
	v_mfma_f32_16x16x32_bf16 v[16:19], v[174:177], v[198:201], v[16:19]
	v_mfma_f32_16x16x32_bf16 v[4:7], v[166:169], v[206:209], v[4:7]
	v_mfma_f32_16x16x32_bf16 v[0:3], v[174:177], v[206:209], v[0:3]
	v_mfma_f32_16x16x32_bf16 v[52:55], v[170:173], v[186:189], v[52:55]
	v_mfma_f32_16x16x32_bf16 v[48:51], v[178:181], v[186:189], v[48:51]
	v_mfma_f32_16x16x32_bf16 v[36:39], v[170:173], v[194:197], v[36:39]
	v_mfma_f32_16x16x32_bf16 v[32:35], v[178:181], v[194:197], v[32:35]
	v_mfma_f32_16x16x32_bf16 v[20:23], v[170:173], v[202:205], v[20:23]
	v_mfma_f32_16x16x32_bf16 v[16:19], v[178:181], v[202:205], v[16:19]
	v_mfma_f32_16x16x32_bf16 v[4:7], v[170:173], v[210:213], v[4:7]
	v_mfma_f32_16x16x32_bf16 v[0:3], v[178:181], v[210:213], v[0:3]
	s_setprio 0
	s_barrier
	ds_read_b128 v[142:145], v151
	ds_read_b128 v[154:157], v151 offset:1024
	ds_read_b128 v[158:161], v151 offset:2048
	ds_read_b128 v[162:165], v151 offset:3072
	ds_read_b128 v[166:169], v152
	ds_read_b128 v[170:173], v152 offset:1024
	ds_read_b128 v[174:177], v152 offset:2048
	ds_read_b128 v[178:181], v152 offset:3072
	s_add_u32 s26, s26, 0x100000
	s_addc_u32 s27, s27, 0
	s_mov_b32 m0, s31
	v_lshl_add_u64 v[222:223], s[26:27], 0, v[128:129]
	ds_read_b128 v[182:185], v150 offset:32768
	ds_read_b128 v[186:189], v150 offset:33792
	ds_read_b128 v[190:193], v150 offset:34816
	ds_read_b128 v[194:197], v150 offset:35840
	ds_read_b128 v[198:201], v150 offset:36864
	ds_read_b128 v[202:205], v150 offset:37888
	ds_read_b128 v[206:209], v150 offset:38912
	ds_read_b128 v[210:213], v150 offset:39936
	global_load_lds_dwordx4 v[222:223], off
	v_lshl_add_u64 v[222:223], s[26:27], 0, v[132:133]
	s_mov_b32 m0, s33
	s_nop 0
	global_load_lds_dwordx4 v[222:223], off
	s_waitcnt vmcnt(8)
	s_waitcnt lgkmcnt(0)
	s_barrier
	s_setprio 1
	s_waitcnt lgkmcnt(0)
	v_mfma_f32_16x16x32_bf16 v[124:127], v[142:145], v[182:185], v[124:127]
	v_mfma_f32_16x16x32_bf16 v[120:123], v[158:161], v[182:185], v[120:123]
	v_mfma_f32_16x16x32_bf16 v[108:111], v[142:145], v[190:193], v[108:111]
	v_mfma_f32_16x16x32_bf16 v[104:107], v[158:161], v[190:193], v[104:107]
	v_mfma_f32_16x16x32_bf16 v[92:95], v[142:145], v[198:201], v[92:95]
	v_mfma_f32_16x16x32_bf16 v[88:91], v[158:161], v[198:201], v[88:91]
	v_mfma_f32_16x16x32_bf16 v[76:79], v[142:145], v[206:209], v[76:79]
	v_mfma_f32_16x16x32_bf16 v[72:75], v[158:161], v[206:209], v[72:75]
	v_mfma_f32_16x16x32_bf16 v[124:127], v[154:157], v[186:189], v[124:127]
	v_mfma_f32_16x16x32_bf16 v[120:123], v[162:165], v[186:189], v[120:123]
	v_mfma_f32_16x16x32_bf16 v[108:111], v[154:157], v[194:197], v[108:111]
	v_mfma_f32_16x16x32_bf16 v[104:107], v[162:165], v[194:197], v[104:107]
	v_mfma_f32_16x16x32_bf16 v[92:95], v[154:157], v[202:205], v[92:95]
	v_mfma_f32_16x16x32_bf16 v[88:91], v[162:165], v[202:205], v[88:91]
	v_mfma_f32_16x16x32_bf16 v[76:79], v[154:157], v[210:213], v[76:79]
	v_mfma_f32_16x16x32_bf16 v[72:75], v[162:165], v[210:213], v[72:75]
	s_setprio 0
	s_setprio 1
	v_mfma_f32_16x16x32_bf16 v[116:119], v[166:169], v[182:185], v[116:119]
	v_mfma_f32_16x16x32_bf16 v[112:115], v[174:177], v[182:185], v[112:115]
	v_mfma_f32_16x16x32_bf16 v[100:103], v[166:169], v[190:193], v[100:103]
	v_mfma_f32_16x16x32_bf16 v[96:99], v[174:177], v[190:193], v[96:99]
	v_mfma_f32_16x16x32_bf16 v[84:87], v[166:169], v[198:201], v[84:87]
	v_mfma_f32_16x16x32_bf16 v[80:83], v[174:177], v[198:201], v[80:83]
	v_mfma_f32_16x16x32_bf16 v[68:71], v[166:169], v[206:209], v[68:71]
	v_mfma_f32_16x16x32_bf16 v[64:67], v[174:177], v[206:209], v[64:67]
	v_mfma_f32_16x16x32_bf16 v[116:119], v[170:173], v[186:189], v[116:119]
	v_mfma_f32_16x16x32_bf16 v[112:115], v[178:181], v[186:189], v[112:115]
	v_mfma_f32_16x16x32_bf16 v[100:103], v[170:173], v[194:197], v[100:103]
	v_mfma_f32_16x16x32_bf16 v[96:99], v[178:181], v[194:197], v[96:99]
	v_mfma_f32_16x16x32_bf16 v[84:87], v[170:173], v[202:205], v[84:87]
	v_mfma_f32_16x16x32_bf16 v[80:83], v[178:181], v[202:205], v[80:83]
	v_mfma_f32_16x16x32_bf16 v[68:71], v[170:173], v[210:213], v[68:71]
	v_mfma_f32_16x16x32_bf16 v[64:67], v[178:181], v[210:213], v[64:67]
	s_setprio 0
	s_barrier
; #define PG8_STAGE(bufoff, gbase, voff) do { _Pragma("unroll") for (int _i = 0; _i < 2; ++_i) \
;         __builtin_amdgcn_global_load_lds((const unsigned*)((const char*)(gbase) + (voff)[_i]), (PG8_LAS unsigned*)(lds + (bufoff) + ldsw + _i * 8192), 16, 0, 0); } while (0)
; #define PG8_LDA(dst, b, h) do { _Pragma("unroll") for (int m = 0; m < 4; ++m) _Pragma("unroll") for (int k = 0; k < 2; ++k) dst[m][k] = *(const PG8_LAS bf16x8*)(lds + PG8_SA(b, h) + aoff + m * 2048 + k * 1024); } while (0)
; #define PG8_MMA(ai, bj, At, Bt) do { __builtin_amdgcn_s_setprio(1); _Pragma("unroll") for (int m = 0; m < 4; ++m) _Pragma("unroll") for (int n = 0; n < 2; ++n) _Pragma("unroll") for (int k = 0; k < 2; ++k) \
;         acc[ai][bj][m][n] = __builtin_amdgcn_mfma_f32_16x16x32_bf16(Bt[n][k], At[m][k], acc[ai][bj][m][n], 0, 0, 0); __builtin_amdgcn_s_setprio(0); } while (0)
; #define PG8_WAIT_V(n) asm volatile("s_waitcnt vmcnt(" #n ")" ::: "memory")
; #define PG8_WAIT_L(n) asm volatile("s_waitcnt lgkmcnt(" #n ")" ::: "memory")
; #define PG8_BAR __builtin_amdgcn_s_barrier()
; #define PG8_SCHED __builtin_amdgcn_sched_barrier(0)
;     __device__ __forceinline__ void operator()(const f32x4 (&acc)[2][2][4][2], const Unit& u, int wr, int wc, int fr, int fq) const {
;         const int col0 = u.pn * BM + wc * 32 + 8 * fq;
; #pragma unroll
;         for (int ai = 0; ai < 2; ++ai)
; #pragma unroll
;             for (int m = 0; m < 4; ++m) { const int r = u.pm * BM + ai * HALF + wr * 64 + m * 16 + fr; const size_t off = (size_t)r * 1024 + col0;
; #pragma unroll
;                 for (int bj = 0; bj < 2; ++bj) { const u32x4 w = __builtin_nontemporal_load((const u32x4*)(xb + off + bj * HALF));
; template <class Epi, class Sched, bool ALIGN_EPI = false, bool SP2 = false>
; __device__ __forceinline__ void gemm_phase(PG8_LAS unsigned char* lds, const Gemm g, const Sched& S, const Epi& E) {
;     ...
;             PG8_LDA(At, 1, 1); PG8_STAGE(PG8_SB(1, 0), b3, voffB); PG8_STAGE(PG8_SB(1, 1), b3 + hstep, voffB); PG8_STAGE(PG8_SA(1, 0), a3, voffA);
;             PG8_WAIT_V(8); PG8_WAIT_L(0); PG8_BAR; PG8_MMA(1, 0, At, B0); PG8_MMA(1, 1, At, B1); PG8_BAR; PG8_SCHED;
	s_add_i32 s26, s39, s29
	v_lshl_add_u64 v[214:215], v[214:215], 0, s[4:5]
	s_mov_b32 m0, s26
	ds_read_b128 v[182:185], v150 offset:49152
	ds_read_b128 v[186:189], v150 offset:50176
	ds_read_b128 v[190:193], v150 offset:51200
	ds_read_b128 v[194:197], v150 offset:52224
	ds_read_b128 v[198:201], v150 offset:53248
	ds_read_b128 v[202:205], v150 offset:54272
	ds_read_b128 v[206:209], v150 offset:55296
	ds_read_b128 v[210:213], v150 offset:56320
	global_load_lds_dwordx4 v[214:215], off
	s_add_i32 m0, s26, 0x2000
	s_add_u32 s24, s24, 0x100080
	v_lshl_add_u64 v[214:215], v[216:217], 0, s[4:5]
	s_addc_u32 s25, s25, 0
	s_add_i32 s26, s40, s29
	global_load_lds_dwordx4 v[214:215], off
	v_lshl_add_u64 v[214:215], s[24:25], 0, v[130:131]
	s_mov_b32 m0, s26
	s_nop 0
	global_load_lds_dwordx4 v[214:215], off
	v_lshl_add_u64 v[214:215], s[24:25], 0, v[134:135]
	s_add_i32 m0, s26, 0x2000
	s_nop 0
	global_load_lds_dwordx4 v[214:215], off
	v_lshl_add_u64 v[214:215], v[218:219], 0, s[4:5]
	s_mov_b32 m0, s34
	s_nop 0
	global_load_lds_dwordx4 v[214:215], off
	v_lshl_add_u64 v[214:215], v[220:221], 0, s[4:5]
	s_mov_b32 m0, s35
	s_nop 0
	global_load_lds_dwordx4 v[214:215], off
	s_waitcnt vmcnt(8)
	s_waitcnt lgkmcnt(0)
	s_barrier
	s_setprio 1
	s_waitcnt lgkmcnt(0)
	v_mfma_f32_16x16x32_bf16 v[60:63], v[142:145], v[182:185], v[60:63]
	v_mfma_f32_16x16x32_bf16 v[56:59], v[158:161], v[182:185], v[56:59]
	v_mfma_f32_16x16x32_bf16 v[44:47], v[142:145], v[190:193], v[44:47]
	v_mfma_f32_16x16x32_bf16 v[40:43], v[158:161], v[190:193], v[40:43]
	v_mfma_f32_16x16x32_bf16 v[28:31], v[142:145], v[198:201], v[28:31]
	v_mfma_f32_16x16x32_bf16 v[24:27], v[158:161], v[198:201], v[24:27]
	v_mfma_f32_16x16x32_bf16 v[12:15], v[142:145], v[206:209], v[12:15]
	v_mfma_f32_16x16x32_bf16 v[8:11], v[158:161], v[206:209], v[8:11]
	v_mfma_f32_16x16x32_bf16 v[60:63], v[154:157], v[186:189], v[60:63]
	v_mfma_f32_16x16x32_bf16 v[56:59], v[162:165], v[186:189], v[56:59]
	v_mfma_f32_16x16x32_bf16 v[44:47], v[154:157], v[194:197], v[44:47]
	v_mfma_f32_16x16x32_bf16 v[40:43], v[162:165], v[194:197], v[40:43]
	v_mfma_f32_16x16x32_bf16 v[28:31], v[154:157], v[202:205], v[28:31]
	v_mfma_f32_16x16x32_bf16 v[24:27], v[162:165], v[202:205], v[24:27]
	v_mfma_f32_16x16x32_bf16 v[12:15], v[154:157], v[210:213], v[12:15]
	v_mfma_f32_16x16x32_bf16 v[8:11], v[162:165], v[210:213], v[8:11]
	s_setprio 0
	s_setprio 1
	v_mfma_f32_16x16x32_bf16 v[52:55], v[166:169], v[182:185], v[52:55]
	v_mfma_f32_16x16x32_bf16 v[48:51], v[174:177], v[182:185], v[48:51]
	v_mfma_f32_16x16x32_bf16 v[36:39], v[166:169], v[190:193], v[36:39]
	v_mfma_f32_16x16x32_bf16 v[32:35], v[174:177], v[190:193], v[32:35]
	v_mfma_f32_16x16x32_bf16 v[20:23], v[166:169], v[198:201], v[20:23]
	v_mfma_f32_16x16x32_bf16 v[16:19], v[174:177], v[198:201], v[16:19]
	v_mfma_f32_16x16x32_bf16 v[4:7], v[166:169], v[206:209], v[4:7]
	v_mfma_f32_16x16x32_bf16 v[0:3], v[174:177], v[206:209], v[0:3]
	v_mfma_f32_16x16x32_bf16 v[52:55], v[170:173], v[186:189], v[52:55]
	v_mfma_f32_16x16x32_bf16 v[48:51], v[178:181], v[186:189], v[48:51]
	v_mfma_f32_16x16x32_bf16 v[36:39], v[170:173], v[194:197], v[36:39]
	v_mfma_f32_16x16x32_bf16 v[32:35], v[178:181], v[194:197], v[32:35]
	v_mfma_f32_16x16x32_bf16 v[20:23], v[170:173], v[202:205], v[20:23]
	v_mfma_f32_16x16x32_bf16 v[16:19], v[178:181], v[202:205], v[16:19]
	v_mfma_f32_16x16x32_bf16 v[4:7], v[170:173], v[210:213], v[4:7]
	v_mfma_f32_16x16x32_bf16 v[0:3], v[178:181], v[210:213], v[0:3]
	s_setprio 0
	s_barrier
	s_add_i32 s47, s47, 2
	s_add_u32 s22, s22, 0x100
	s_addc_u32 s23, s23, 0
	s_add_u32 s45, s45, 0x100
	s_addc_u32 s46, s46, 0
	s_cmp_gt_u32 s47, 61
	s_cbranch_scc0 .LBB0_1498
	v_lshl_add_u32 v144, s20, 8, v146
	v_lshl_or_b32 v142, s18, 8, v147
	v_ashrrev_i32_e32 v145, 31, v144
	v_ashrrev_i32_e32 v143, 31, v142
	v_lshlrev_b64 v[228:229], 10, v[144:145]
	v_lshl_add_u64 v[228:229], v[228:229], 0, v[142:143]
	v_lshl_add_u64 v[236:237], v[228:229], 1, s[66:67]
	v_lshl_add_u64 v[238:239], v[228:229], 2, s[60:61]
	s_mov_b64 s[70:71], 0x8000
	s_mov_b64 s[72:73], 0x28000
	s_mov_b64 s[74:75], 0x10000
	s_mov_b64 s[76:77], 0x50000
	global_load_dwordx4 v[154:157], v[236:237], off nt
	global_load_dwordx4 v[158:161], v[236:237], off offset:256 nt
	v_lshl_add_u64 v[236:237], v[236:237], 0, s[70:71]
	global_load_dwordx4 v[162:165], v[236:237], off nt
	global_load_dwordx4 v[166:169], v[236:237], off offset:256 nt
	v_lshl_add_u64 v[236:237], v[236:237], 0, s[70:71]
	global_load_dwordx4 v[170:173], v[236:237], off nt
	global_load_dwordx4 v[174:177], v[236:237], off offset:256 nt
	v_lshl_add_u64 v[236:237], v[236:237], 0, s[70:71]
	global_load_dwordx4 v[178:181], v[236:237], off nt
	global_load_dwordx4 v[182:185], v[236:237], off offset:256 nt
	v_lshl_add_u64 v[236:237], v[236:237], 0, s[72:73]
	global_load_dwordx4 v[186:189], v[236:237], off nt
	global_load_dwordx4 v[190:193], v[236:237], off offset:256 nt
	v_lshl_add_u64 v[236:237], v[236:237], 0, s[70:71]
	global_load_dwordx4 v[194:197], v[236:237], off nt
	global_load_dwordx4 v[198:201], v[236:237], off offset:256 nt
	v_lshl_add_u64 v[236:237], v[236:237], 0, s[70:71]
	global_load_dwordx4 v[202:205], v[236:237], off nt
	global_load_dwordx4 v[206:209], v[236:237], off offset:256 nt
	v_lshl_add_u64 v[236:237], v[236:237], 0, s[70:71]
	global_load_dwordx4 v[210:213], v[236:237], off nt
	global_load_dwordx4 v[224:227], v[236:237], off offset:256 nt
	s_and_b64 vcc, exec, s[6:7]
	s_cbranch_vccz .LBB0_1501
	s_barrier
;     __device__ __forceinline__ void operator()(const f32x4 (&acc)[2][2][4][2], const Unit& u, int wr, int wc, int fr, int fq) const {
;     ...
;             for (int m = 0; m < 4; ++m) { const int r = u.pm * BM + ai * HALF + wr * 64 + m * 16 + fr; const size_t off = (size_t)r * 1024 + col0;
; #pragma unroll
;                 for (int bj = 0; bj < 2; ++bj) { const u32x4 w = __builtin_nontemporal_load((const u32x4*)(xb + off + bj * HALF));
;                     const f32x4 b0 = {__builtin_bit_cast(float, w.x << 16), __builtin_bit_cast(float, w.x & 0xffff0000u), __builtin_bit_cast(float, w.y << 16), __builtin_bit_cast(float, w.y & 0xffff0000u)};
;                     const f32x4 b1 = {__builtin_bit_cast(float, w.z << 16), __builtin_bit_cast(float, w.z & 0xffff0000u), __builtin_bit_cast(float, w.w << 16), __builtin_bit_cast(float, w.w & 0xffff0000u)};
;                     __builtin_nontemporal_store(b0 + acc[ai][bj][m][0], (f32x4*)(out + off + bj * HALF)); __builtin_nontemporal_store(b1 + acc[ai][bj][m][1], (f32x4*)(out + off + bj * HALF + 4)); } }
.LBB0_1501:
	s_waitcnt vmcnt(15)
	v_lshlrev_b32_e32 v228, 16, v154
	v_and_b32_e32 v229, 0xffff0000, v154
	v_lshlrev_b32_e32 v230, 16, v155
	v_and_b32_e32 v231, 0xffff0000, v155
	v_lshlrev_b32_e32 v232, 16, v156
	v_and_b32_e32 v233, 0xffff0000, v156
	v_lshlrev_b32_e32 v234, 16, v157
	v_and_b32_e32 v235, 0xffff0000, v157
	v_pk_add_f32 v[124:125], v[124:125], v[228:229]
	v_pk_add_f32 v[126:127], v[126:127], v[230:231]
	v_pk_add_f32 v[120:121], v[120:121], v[232:233]
	v_pk_add_f32 v[122:123], v[122:123], v[234:235]
	global_store_dwordx4 v[238:239], v[124:127], off nt
	global_store_dwordx4 v[238:239], v[120:123], off offset:16 nt
	s_waitcnt vmcnt(16)
	v_lshlrev_b32_e32 v228, 16, v158
	v_and_b32_e32 v229, 0xffff0000, v158
	v_lshlrev_b32_e32 v230, 16, v159
	v_and_b32_e32 v231, 0xffff0000, v159
	v_lshlrev_b32_e32 v232, 16, v160
	v_and_b32_e32 v233, 0xffff0000, v160
	v_lshlrev_b32_e32 v234, 16, v161
	v_and_b32_e32 v235, 0xffff0000, v161
	v_pk_add_f32 v[116:117], v[116:117], v[228:229]
	v_pk_add_f32 v[118:119], v[118:119], v[230:231]
	v_pk_add_f32 v[112:113], v[112:113], v[232:233]
	v_pk_add_f32 v[114:115], v[114:115], v[234:235]
	global_store_dwordx4 v[238:239], v[116:119], off offset:512 nt
	global_store_dwordx4 v[238:239], v[112:115], off offset:528 nt
	v_lshl_add_u64 v[238:239], v[238:239], 0, s[74:75]
	s_waitcnt vmcnt(17)
	v_lshlrev_b32_e32 v228, 16, v162
	v_and_b32_e32 v229, 0xffff0000, v162
	v_lshlrev_b32_e32 v230, 16, v163
	v_and_b32_e32 v231, 0xffff0000, v163
	v_lshlrev_b32_e32 v232, 16, v164
	v_and_b32_e32 v233, 0xffff0000, v164
	v_lshlrev_b32_e32 v234, 16, v165
	v_and_b32_e32 v235, 0xffff0000, v165
	v_pk_add_f32 v[108:109], v[108:109], v[228:229]
	v_pk_add_f32 v[110:111], v[110:111], v[230:231]
	v_pk_add_f32 v[104:105], v[104:105], v[232:233]
	v_pk_add_f32 v[106:107], v[106:107], v[234:235]
	global_store_dwordx4 v[238:239], v[108:111], off nt
	global_store_dwordx4 v[238:239], v[104:107], off offset:16 nt
	s_waitcnt vmcnt(18)
	v_lshlrev_b32_e32 v228, 16, v166
	v_and_b32_e32 v229, 0xffff0000, v166
	v_lshlrev_b32_e32 v230, 16, v167
	v_and_b32_e32 v231, 0xffff0000, v167
	v_lshlrev_b32_e32 v232, 16, v168
	v_and_b32_e32 v233, 0xffff0000, v168
	v_lshlrev_b32_e32 v234, 16, v169
	v_and_b32_e32 v235, 0xffff0000, v169
	v_pk_add_f32 v[100:101], v[100:101], v[228:229]
	v_pk_add_f32 v[102:103], v[102:103], v[230:231]
	v_pk_add_f32 v[96:97], v[96:97], v[232:233]
	v_pk_add_f32 v[98:99], v[98:99], v[234:235]
	global_store_dwordx4 v[238:239], v[100:103], off offset:512 nt
	global_store_dwordx4 v[238:239], v[96:99], off offset:528 nt
	v_lshl_add_u64 v[238:239], v[238:239], 0, s[74:75]
	s_waitcnt vmcnt(19)
	v_lshlrev_b32_e32 v228, 16, v170
	v_and_b32_e32 v229, 0xffff0000, v170
	v_lshlrev_b32_e32 v230, 16, v171
	v_and_b32_e32 v231, 0xffff0000, v171
	v_lshlrev_b32_e32 v232, 16, v172
	v_and_b32_e32 v233, 0xffff0000, v172
	v_lshlrev_b32_e32 v234, 16, v173
	v_and_b32_e32 v235, 0xffff0000, v173
	v_pk_add_f32 v[92:93], v[92:93], v[228:229]
	v_pk_add_f32 v[94:95], v[94:95], v[230:231]
	v_pk_add_f32 v[88:89], v[88:89], v[232:233]
	v_pk_add_f32 v[90:91], v[90:91], v[234:235]
	global_store_dwordx4 v[238:239], v[92:95], off nt
	global_store_dwordx4 v[238:239], v[88:91], off offset:16 nt
	s_waitcnt vmcnt(20)
	v_lshlrev_b32_e32 v228, 16, v174
	v_and_b32_e32 v229, 0xffff0000, v174
	v_lshlrev_b32_e32 v230, 16, v175
	v_and_b32_e32 v231, 0xffff0000, v175
	v_lshlrev_b32_e32 v232, 16, v176
	v_and_b32_e32 v233, 0xffff0000, v176
	v_lshlrev_b32_e32 v234, 16, v177
	v_and_b32_e32 v235, 0xffff0000, v177
	v_pk_add_f32 v[84:85], v[84:85], v[228:229]
	v_pk_add_f32 v[86:87], v[86:87], v[230:231]
	v_pk_add_f32 v[80:81], v[80:81], v[232:233]
	v_pk_add_f32 v[82:83], v[82:83], v[234:235]
	global_store_dwordx4 v[238:239], v[84:87], off offset:512 nt
	global_store_dwordx4 v[238:239], v[80:83], off offset:528 nt
	v_lshl_add_u64 v[238:239], v[238:239], 0, s[74:75]
	s_waitcnt vmcnt(21)
	v_lshlrev_b32_e32 v228, 16, v178
	v_and_b32_e32 v229, 0xffff0000, v178
	v_lshlrev_b32_e32 v230, 16, v179
	v_and_b32_e32 v231, 0xffff0000, v179
	v_lshlrev_b32_e32 v232, 16, v180
	v_and_b32_e32 v233, 0xffff0000, v180
	v_lshlrev_b32_e32 v234, 16, v181
	v_and_b32_e32 v235, 0xffff0000, v181
	v_pk_add_f32 v[76:77], v[76:77], v[228:229]
	v_pk_add_f32 v[78:79], v[78:79], v[230:231]
	v_pk_add_f32 v[72:73], v[72:73], v[232:233]
	v_pk_add_f32 v[74:75], v[74:75], v[234:235]
	global_store_dwordx4 v[238:239], v[76:79], off nt
	global_store_dwordx4 v[238:239], v[72:75], off offset:16 nt
	s_waitcnt vmcnt(22)
	v_lshlrev_b32_e32 v228, 16, v182
	v_and_b32_e32 v229, 0xffff0000, v182
	v_lshlrev_b32_e32 v230, 16, v183
	v_and_b32_e32 v231, 0xffff0000, v183
	v_lshlrev_b32_e32 v232, 16, v184
	v_and_b32_e32 v233, 0xffff0000, v184
	v_lshlrev_b32_e32 v234, 16, v185
	v_and_b32_e32 v235, 0xffff0000, v185
	v_pk_add_f32 v[68:69], v[68:69], v[228:229]
	v_pk_add_f32 v[70:71], v[70:71], v[230:231]
	v_pk_add_f32 v[64:65], v[64:65], v[232:233]
	v_pk_add_f32 v[66:67], v[66:67], v[234:235]
	global_store_dwordx4 v[238:239], v[68:71], off offset:512 nt
	global_store_dwordx4 v[238:239], v[64:67], off offset:528 nt
	v_lshl_add_u64 v[238:239], v[238:239], 0, s[76:77]
	s_waitcnt vmcnt(23)
;     __device__ __forceinline__ void operator()(const f32x4 (&acc)[2][2][4][2], const Unit& u, int wr, int wc, int fr, int fq) const {
;     ...
;             for (int m = 0; m < 4; ++m) { const int r = u.pm * BM + ai * HALF + wr * 64 + m * 16 + fr; const size_t off = (size_t)r * 1024 + col0;
; #pragma unroll
;                 for (int bj = 0; bj < 2; ++bj) { const u32x4 w = __builtin_nontemporal_load((const u32x4*)(xb + off + bj * HALF));
;                     const f32x4 b0 = {__builtin_bit_cast(float, w.x << 16), __builtin_bit_cast(float, w.x & 0xffff0000u), __builtin_bit_cast(float, w.y << 16), __builtin_bit_cast(float, w.y & 0xffff0000u)};
;                     const f32x4 b1 = {__builtin_bit_cast(float, w.z << 16), __builtin_bit_cast(float, w.z & 0xffff0000u), __builtin_bit_cast(float, w.w << 16), __builtin_bit_cast(float, w.w & 0xffff0000u)};
;                     __builtin_nontemporal_store(b0 + acc[ai][bj][m][0], (f32x4*)(out + off + bj * HALF)); __builtin_nontemporal_store(b1 + acc[ai][bj][m][1], (f32x4*)(out + off + bj * HALF + 4)); } }
; template <class Epi, class Sched, bool ALIGN_EPI = false, bool SP2 = false>
; __device__ __forceinline__ void gemm_phase(PG8_LAS unsigned char* lds, const Gemm g, const Sched& S, const Epi& E) {
;     ...
;         if (!has_next) break;
	v_lshlrev_b32_e32 v228, 16, v186
	v_and_b32_e32 v229, 0xffff0000, v186
	v_lshlrev_b32_e32 v230, 16, v187
	v_and_b32_e32 v231, 0xffff0000, v187
	v_lshlrev_b32_e32 v232, 16, v188
	v_and_b32_e32 v233, 0xffff0000, v188
	v_lshlrev_b32_e32 v234, 16, v189
	v_and_b32_e32 v235, 0xffff0000, v189
	v_pk_add_f32 v[60:61], v[60:61], v[228:229]
	v_pk_add_f32 v[62:63], v[62:63], v[230:231]
	v_pk_add_f32 v[56:57], v[56:57], v[232:233]
	v_pk_add_f32 v[58:59], v[58:59], v[234:235]
	global_store_dwordx4 v[238:239], v[60:63], off nt
	global_store_dwordx4 v[238:239], v[56:59], off offset:16 nt
	s_waitcnt vmcnt(24)
	v_lshlrev_b32_e32 v228, 16, v190
	v_and_b32_e32 v229, 0xffff0000, v190
	v_lshlrev_b32_e32 v230, 16, v191
	v_and_b32_e32 v231, 0xffff0000, v191
	v_lshlrev_b32_e32 v232, 16, v192
	v_and_b32_e32 v233, 0xffff0000, v192
	v_lshlrev_b32_e32 v234, 16, v193
	v_and_b32_e32 v235, 0xffff0000, v193
	v_pk_add_f32 v[52:53], v[52:53], v[228:229]
	v_pk_add_f32 v[54:55], v[54:55], v[230:231]
	v_pk_add_f32 v[48:49], v[48:49], v[232:233]
	v_pk_add_f32 v[50:51], v[50:51], v[234:235]
	global_store_dwordx4 v[238:239], v[52:55], off offset:512 nt
	global_store_dwordx4 v[238:239], v[48:51], off offset:528 nt
	v_lshl_add_u64 v[238:239], v[238:239], 0, s[74:75]
	s_waitcnt vmcnt(25)
	v_lshlrev_b32_e32 v228, 16, v194
	v_and_b32_e32 v229, 0xffff0000, v194
	v_lshlrev_b32_e32 v230, 16, v195
	v_and_b32_e32 v231, 0xffff0000, v195
	v_lshlrev_b32_e32 v232, 16, v196
	v_and_b32_e32 v233, 0xffff0000, v196
	v_lshlrev_b32_e32 v234, 16, v197
	v_and_b32_e32 v235, 0xffff0000, v197
	v_pk_add_f32 v[44:45], v[44:45], v[228:229]
	v_pk_add_f32 v[46:47], v[46:47], v[230:231]
	v_pk_add_f32 v[40:41], v[40:41], v[232:233]
	v_pk_add_f32 v[42:43], v[42:43], v[234:235]
	global_store_dwordx4 v[238:239], v[44:47], off nt
	global_store_dwordx4 v[238:239], v[40:43], off offset:16 nt
	s_waitcnt vmcnt(26)
	v_lshlrev_b32_e32 v228, 16, v198
	v_and_b32_e32 v229, 0xffff0000, v198
	v_lshlrev_b32_e32 v230, 16, v199
	v_and_b32_e32 v231, 0xffff0000, v199
	v_lshlrev_b32_e32 v232, 16, v200
	v_and_b32_e32 v233, 0xffff0000, v200
	v_lshlrev_b32_e32 v234, 16, v201
	v_and_b32_e32 v235, 0xffff0000, v201
	v_pk_add_f32 v[36:37], v[36:37], v[228:229]
	v_pk_add_f32 v[38:39], v[38:39], v[230:231]
	v_pk_add_f32 v[32:33], v[32:33], v[232:233]
	v_pk_add_f32 v[34:35], v[34:35], v[234:235]
	global_store_dwordx4 v[238:239], v[36:39], off offset:512 nt
	global_store_dwordx4 v[238:239], v[32:35], off offset:528 nt
	v_lshl_add_u64 v[238:239], v[238:239], 0, s[74:75]
	s_waitcnt vmcnt(27)
	v_lshlrev_b32_e32 v228, 16, v202
	v_and_b32_e32 v229, 0xffff0000, v202
	v_lshlrev_b32_e32 v230, 16, v203
	v_and_b32_e32 v231, 0xffff0000, v203
	v_lshlrev_b32_e32 v232, 16, v204
	v_and_b32_e32 v233, 0xffff0000, v204
	v_lshlrev_b32_e32 v234, 16, v205
	v_and_b32_e32 v235, 0xffff0000, v205
	v_pk_add_f32 v[28:29], v[28:29], v[228:229]
	v_pk_add_f32 v[30:31], v[30:31], v[230:231]
	v_pk_add_f32 v[24:25], v[24:25], v[232:233]
	v_pk_add_f32 v[26:27], v[26:27], v[234:235]
	global_store_dwordx4 v[238:239], v[28:31], off nt
	global_store_dwordx4 v[238:239], v[24:27], off offset:16 nt
	s_waitcnt vmcnt(28)
	v_lshlrev_b32_e32 v228, 16, v206
	v_and_b32_e32 v229, 0xffff0000, v206
	v_lshlrev_b32_e32 v230, 16, v207
	v_and_b32_e32 v231, 0xffff0000, v207
	v_lshlrev_b32_e32 v232, 16, v208
	v_and_b32_e32 v233, 0xffff0000, v208
	v_lshlrev_b32_e32 v234, 16, v209
	v_and_b32_e32 v235, 0xffff0000, v209
	v_pk_add_f32 v[20:21], v[20:21], v[228:229]
	v_pk_add_f32 v[22:23], v[22:23], v[230:231]
	v_pk_add_f32 v[16:17], v[16:17], v[232:233]
	v_pk_add_f32 v[18:19], v[18:19], v[234:235]
	global_store_dwordx4 v[238:239], v[20:23], off offset:512 nt
	global_store_dwordx4 v[238:239], v[16:19], off offset:528 nt
	v_lshl_add_u64 v[238:239], v[238:239], 0, s[74:75]
	s_waitcnt vmcnt(29)
	v_lshlrev_b32_e32 v228, 16, v210
	v_and_b32_e32 v229, 0xffff0000, v210
	v_lshlrev_b32_e32 v230, 16, v211
	v_and_b32_e32 v231, 0xffff0000, v211
	v_lshlrev_b32_e32 v232, 16, v212
	v_and_b32_e32 v233, 0xffff0000, v212
	v_lshlrev_b32_e32 v234, 16, v213
	v_and_b32_e32 v235, 0xffff0000, v213
	v_pk_add_f32 v[12:13], v[12:13], v[228:229]
	v_pk_add_f32 v[14:15], v[14:15], v[230:231]
	v_pk_add_f32 v[8:9], v[8:9], v[232:233]
	v_pk_add_f32 v[10:11], v[10:11], v[234:235]
	global_store_dwordx4 v[238:239], v[12:15], off nt
	global_store_dwordx4 v[238:239], v[8:11], off offset:16 nt
	s_waitcnt vmcnt(30)
	v_lshlrev_b32_e32 v228, 16, v224
	v_and_b32_e32 v229, 0xffff0000, v224
	v_lshlrev_b32_e32 v230, 16, v225
	v_and_b32_e32 v231, 0xffff0000, v225
	v_lshlrev_b32_e32 v232, 16, v226
	v_and_b32_e32 v233, 0xffff0000, v226
	v_lshlrev_b32_e32 v234, 16, v227
	v_and_b32_e32 v235, 0xffff0000, v227
	v_pk_add_f32 v[4:5], v[4:5], v[228:229]
	v_pk_add_f32 v[6:7], v[6:7], v[230:231]
	v_pk_add_f32 v[0:1], v[0:1], v[232:233]
	v_pk_add_f32 v[2:3], v[2:3], v[234:235]
	global_store_dwordx4 v[238:239], v[4:7], off offset:512 nt
	global_store_dwordx4 v[238:239], v[0:3], off offset:528 nt
	s_andn2_b64 vcc, exec, s[14:15]
	s_mov_b64 s[14:15], -1
	s_cbranch_vccnz .LBB0_1493
	s_andn2_b64 vcc, exec, s[0:1]
	s_cbranch_vccnz .LBB0_1492
	s_barrier
	s_branch .LBB0_1492

; __global__ void __launch_bounds__(NWAVES * 64, 2) mega_fwd(Args args) {
;     extern __shared__ __attribute__((aligned(16))) unsigned char lds[];
	.amdhsa_kernel _Z8mega_fwd4Args
		.amdhsa_group_segment_fixed_size 256
		.amdhsa_private_segment_fixed_size 0
		.amdhsa_kernarg_size 376
		.amdhsa_user_sgpr_count 2
		.amdhsa_user_sgpr_dispatch_ptr 0
		.amdhsa_user_sgpr_queue_ptr 0
		.amdhsa_user_sgpr_kernarg_segment_ptr 1
		.amdhsa_user_sgpr_dispatch_id 0
		.amdhsa_user_sgpr_kernarg_preload_length 0
		.amdhsa_user_sgpr_kernarg_preload_offset 0
		.amdhsa_user_sgpr_private_segment_size 0
		.amdhsa_uses_dynamic_stack 0
		.amdhsa_enable_private_segment 0
		.amdhsa_system_sgpr_workgroup_id_x 1
		.amdhsa_system_sgpr_workgroup_id_y 0
		.amdhsa_system_sgpr_workgroup_id_z 0
		.amdhsa_system_sgpr_workgroup_info 0
		.amdhsa_system_vgpr_workitem_id 2
		.amdhsa_next_free_vgpr 255
		.amdhsa_next_free_sgpr 102
		.amdhsa_accum_offset 256
		.amdhsa_reserve_vcc 1
		.amdhsa_float_round_mode_32 0
		.amdhsa_float_round_mode_16_64 0
		.amdhsa_float_denorm_mode_32 3
		.amdhsa_float_denorm_mode_16_64 3
		.amdhsa_dx10_clamp 1
		.amdhsa_ieee_mode 1
		.amdhsa_fp16_overflow 0
		.amdhsa_tg_split 0
		.amdhsa_exception_fp_ieee_invalid_op 0
		.amdhsa_exception_fp_denorm_src 0
		.amdhsa_exception_fp_ieee_div_zero 0
		.amdhsa_exception_fp_ieee_overflow 0
		.amdhsa_exception_fp_ieee_underflow 0
		.amdhsa_exception_fp_ieee_inexact 0
		.amdhsa_exception_int_div_zero 0
	.end_amdhsa_kernel

; __global__ void __launch_bounds__(NWAVES * 64, 2) mega_fwd(Args args) {
amdhsa.kernels:
  - .agpr_count:     0
    .args:
      - .offset:         0
        .size:           120
        .value_kind:     by_value
      - .offset:         120
        .size:           4
        .value_kind:     hidden_block_count_x
      - .offset:         124
        .size:           4
        .value_kind:     hidden_block_count_y
      - .offset:         128
        .size:           4
        .value_kind:     hidden_block_count_z
      - .offset:         132
        .size:           2
        .value_kind:     hidden_group_size_x
      - .offset:         134
        .size:           2
        .value_kind:     hidden_group_size_y
      - .offset:         136
        .size:           2
        .value_kind:     hidden_group_size_z
      - .offset:         138
        .size:           2
        .value_kind:     hidden_remainder_x
      - .offset:         140
        .size:           2
        .value_kind:     hidden_remainder_y
      - .offset:         142
        .size:           2
        .value_kind:     hidden_remainder_z
      - .offset:         160
        .size:           8
        .value_kind:     hidden_global_offset_x
      - .offset:         168
        .size:           8
        .value_kind:     hidden_global_offset_y
      - .offset:         176
        .size:           8
        .value_kind:     hidden_global_offset_z
      - .offset:         184
        .size:           2
        .value_kind:     hidden_grid_dims
      - .offset:         208
        .size:           8
        .value_kind:     hidden_multigrid_sync_arg
      - .offset:         240
        .size:           4
        .value_kind:     hidden_dynamic_lds_size
    .group_segment_fixed_size: 256
    .kernarg_segment_align: 8
    .kernarg_segment_size: 376
    .language:       OpenCL C
    .language_version:
      - 2
      - 0
    .max_flat_workgroup_size: 512
    .name:           _Z8mega_fwd4Args
    .private_segment_fixed_size: 0
    .sgpr_count:     108
    .sgpr_spill_count: 4
    .symbol:         _Z8mega_fwd4Args.kd
    .uniform_work_group_size: 1
    .uses_dynamic_stack: false
    .vgpr_count:     255
    .vgpr_spill_count: 0
    .wavefront_size: 64
